# accumulator zeroing at the GEMM unit headers with 64-bit moves
# speedup vs baseline: 1.0087x; 1.0071x over previous
; __device__ __forceinline__ int prow0(int pm) { return (pm >> 4) * LP + PADR + (pm & 15) * 256; }
; template <class Epi>
; __device__ __forceinline__ void gemm_phase(LAS unsigned char* lds, const bf16_t* Ag, const bf16_t* Btg, const int K, const int nM, const int nN, const Epi& E) {
;     ...
;         const int un = u + G; const bool has_next = un < nunits; const int pmn = has_next ? un % nM : pm, pnn = has_next ? un / nM : pn;
;         const char* nA = has_next ? (const char*)Ag + (size_t)prow0(pmn) * rstep : cA; const char* nB = has_next ? (const char*)Btg + (size_t)pnn * tstep : cB;
;     ...
; #pragma unroll
;         for (int a = 0; a < 2; ++a)
; #pragma unroll
;             for (int b = 0; b < 2; ++b)
; #pragma unroll
;                 for (int m = 0; m < 4; ++m)
; #pragma unroll
;                     for (int n = 0; n < 2; ++n) acc[a][b][m][n] = (f32x4){0.f, 0.f, 0.f, 0.f};
;         if (pmn != pm) par ^= 1;
;         u = un; pm = pmn; pn = pnn; cA = nA; cB = nB;
.LBB0_76:
	s_ashr_i32 s47, s12, 6
	s_and_b64 s[14:15], s[48:49], exec
	s_cselect_b32 s14, s68, s47
	s_ashr_i32 s15, s14, 31
	s_lshl_b64 s[14:15], s[14:15], 19
	s_add_u32 s44, s24, s14
	s_addc_u32 s45, s25, s15
	s_and_b64 s[14:15], s[48:49], exec
	s_cselect_b32 s15, s53, s45
	s_cselect_b32 s69, s52, s44
	s_cmp_eq_u32 s67, s66
	s_cselect_b64 s[54:55], -1, 0
	s_lshl_b32 s14, s64, 11
	s_xor_b32 s12, s14, 0x800
	s_add_i32 s70, s12, 0
	s_add_i32 s70, s70, 0x20000
	s_or_b64 s[48:49], s[48:49], s[54:55]
	s_add_u32 s71, s52, 0x100
	s_addc_u32 s72, s53, 0
	s_add_u32 s50, s50, 0x40080
	v_mov_b32_e32 v8, 0
	s_addc_u32 s51, s51, 0
	s_mov_b32 s73, -2
	v_mov_b32_e32 v9, 0
	v_mov_b64_e32 v[10:11], 0
	v_mov_b64_e32 v[12:13], 0
	v_mov_b64_e32 v[14:15], 0
	v_mov_b64_e32 v[24:25], 0
	v_mov_b64_e32 v[26:27], 0
	v_mov_b64_e32 v[28:29], 0
	v_mov_b64_e32 v[30:31], 0
	v_mov_b64_e32 v[40:41], 0
	v_mov_b64_e32 v[42:43], 0
	v_mov_b64_e32 v[44:45], 0
	v_mov_b64_e32 v[46:47], 0
	v_mov_b64_e32 v[56:57], 0
	v_mov_b64_e32 v[58:59], 0
	v_mov_b64_e32 v[60:61], 0
	v_mov_b64_e32 v[62:63], 0
	v_mov_b64_e32 v[72:73], 0
	v_mov_b64_e32 v[74:75], 0
	v_mov_b64_e32 v[76:77], 0
	v_mov_b64_e32 v[78:79], 0
	v_mov_b64_e32 v[88:89], 0
	v_mov_b64_e32 v[90:91], 0
	v_mov_b64_e32 v[92:93], 0
	v_mov_b64_e32 v[94:95], 0
	v_mov_b64_e32 v[104:105], 0
	v_mov_b64_e32 v[106:107], 0
	v_mov_b64_e32 v[108:109], 0
	v_mov_b64_e32 v[110:111], 0
	v_mov_b64_e32 v[120:121], 0
	v_mov_b64_e32 v[122:123], 0
	v_mov_b64_e32 v[144:145], 0
	v_mov_b64_e32 v[146:147], 0
	v_mov_b64_e32 v[80:81], 0
	v_mov_b64_e32 v[82:83], 0
	v_mov_b64_e32 v[84:85], 0
	v_mov_b64_e32 v[86:87], 0
	v_mov_b64_e32 v[96:97], 0
	v_mov_b64_e32 v[98:99], 0
	v_mov_b64_e32 v[100:101], 0
	v_mov_b64_e32 v[102:103], 0
	v_mov_b64_e32 v[112:113], 0
	v_mov_b64_e32 v[114:115], 0
	v_mov_b64_e32 v[116:117], 0
	v_mov_b64_e32 v[118:119], 0
	v_mov_b64_e32 v[160:161], 0
	v_mov_b64_e32 v[162:163], 0
	v_mov_b64_e32 v[164:165], 0
	v_mov_b64_e32 v[166:167], 0
	v_mov_b64_e32 v[68:69], 0
	v_mov_b64_e32 v[70:71], 0
	v_mov_b64_e32 v[64:65], 0
	v_mov_b64_e32 v[66:67], 0
	v_mov_b64_e32 v[52:53], 0
	v_mov_b64_e32 v[54:55], 0
	v_mov_b64_e32 v[48:49], 0
	v_mov_b64_e32 v[50:51], 0
	v_mov_b64_e32 v[36:37], 0
	v_mov_b64_e32 v[38:39], 0
	v_mov_b64_e32 v[32:33], 0
	v_mov_b64_e32 v[34:35], 0
	v_mov_b64_e32 v[20:21], 0
	v_mov_b64_e32 v[22:23], 0
	v_mov_b64_e32 v[16:17], 0
	v_mov_b64_e32 v[18:19], 0
	s_branch .LBB0_79

; __device__ __forceinline__ int prow0(int pm) { return (pm >> 4) * LP + PADR + (pm & 15) * 256; }
; template <class Epi>
; __device__ __forceinline__ void gemm_phase(LAS unsigned char* lds, const bf16_t* Ag, const bf16_t* Btg, const int K, const int nM, const int nN, const Epi& E) {
;     ...
;         const int un = u + G; const bool has_next = un < nunits; const int pmn = has_next ? un % nM : pm, pnn = has_next ? un / nM : pn;
;         const char* nA = has_next ? (const char*)Ag + (size_t)prow0(pmn) * rstep : cA; const char* nB = has_next ? (const char*)Btg + (size_t)pnn * tstep : cB;
;     ...
; #pragma unroll
;         for (int a = 0; a < 2; ++a)
; #pragma unroll
;             for (int b = 0; b < 2; ++b)
; #pragma unroll
;                 for (int m = 0; m < 4; ++m)
; #pragma unroll
;                     for (int n = 0; n < 2; ++n) acc[a][b][m][n] = (f32x4){0.f, 0.f, 0.f, 0.f};
;         if (pmn != pm) par ^= 1;
;         u = un; pm = pmn; pn = pnn; cA = nA; cB = nB;
.LBB0_151:
	s_ashr_i32 s56, s12, 6
	s_ashr_i32 s57, s56, 31
	s_lshl_b64 s[14:15], s[56:57], 19
	s_add_u32 s58, s46, s14
	s_addc_u32 s59, s47, s15
	s_and_b64 s[14:15], s[62:63], exec
	s_cselect_b32 s14, s67, s59
	s_cselect_b32 s15, s66, s58
	s_cmp_eq_u32 s79, s96
	s_cselect_b64 s[42:43], -1, 0
	v_lshlrev_b32_e32 v142, 11, v231
	v_xor_b32_e32 v8, 0x800, v142
	s_or_b64 s[42:43], s[62:63], s[42:43]
	v_add_u32_e32 v8, 0, v8
	s_or_b64 s[62:63], s[6:7], s[42:43]
	v_add_u32_e32 v140, 0x20000, v8
	s_add_u32 s57, s66, 0x100
	v_mov_b32_e32 v8, 0
	s_addc_u32 s61, s67, 0
	s_mov_b32 s42, -2
	v_mov_b32_e32 v9, v8
	s_waitcnt lgkmcnt(0)
	v_mov_b64_e32 v[10:11], 0
	v_mov_b64_e32 v[12:13], 0
	v_mov_b64_e32 v[14:15], 0
	v_mov_b64_e32 v[24:25], 0
	v_mov_b64_e32 v[26:27], 0
	v_mov_b64_e32 v[28:29], 0
	v_mov_b64_e32 v[30:31], 0
	v_mov_b64_e32 v[40:41], 0
	v_mov_b64_e32 v[42:43], 0
	v_mov_b64_e32 v[44:45], 0
	v_mov_b64_e32 v[46:47], 0
	v_mov_b64_e32 v[56:57], 0
	v_mov_b64_e32 v[58:59], 0
	v_mov_b64_e32 v[60:61], 0
	v_mov_b64_e32 v[62:63], 0
	v_mov_b64_e32 v[16:17], 0
	v_mov_b64_e32 v[18:19], 0
	v_mov_b64_e32 v[20:21], 0
	v_mov_b64_e32 v[22:23], 0
	v_mov_b64_e32 v[32:33], 0
	v_mov_b64_e32 v[34:35], 0
	v_mov_b64_e32 v[36:37], 0
	v_mov_b64_e32 v[38:39], 0
	v_mov_b64_e32 v[48:49], 0
	v_mov_b64_e32 v[50:51], 0
	v_mov_b64_e32 v[52:53], 0
	v_mov_b64_e32 v[54:55], 0
	v_mov_b64_e32 v[64:65], 0
	v_mov_b64_e32 v[66:67], 0
	v_mov_b64_e32 v[68:69], 0
	v_mov_b64_e32 v[70:71], 0
	v_mov_b64_e32 v[72:73], 0
	v_mov_b64_e32 v[74:75], 0
	v_mov_b64_e32 v[76:77], 0
	v_mov_b64_e32 v[78:79], 0
	v_mov_b64_e32 v[88:89], 0
	v_mov_b64_e32 v[90:91], 0
	v_mov_b64_e32 v[92:93], 0
	v_mov_b64_e32 v[94:95], 0
	v_mov_b64_e32 v[104:105], 0
	v_mov_b64_e32 v[106:107], 0
	v_mov_b64_e32 v[108:109], 0
	v_mov_b64_e32 v[110:111], 0
	v_mov_b64_e32 v[120:121], 0
	v_mov_b64_e32 v[122:123], 0
	v_mov_b64_e32 v[124:125], 0
	v_mov_b64_e32 v[126:127], 0
	v_mov_b64_e32 v[80:81], 0
	v_mov_b64_e32 v[82:83], 0
	v_mov_b64_e32 v[84:85], 0
	v_mov_b64_e32 v[86:87], 0
	v_mov_b64_e32 v[96:97], 0
	v_mov_b64_e32 v[98:99], 0
	v_mov_b64_e32 v[100:101], 0
	v_mov_b64_e32 v[102:103], 0
	v_mov_b64_e32 v[112:113], 0
	v_mov_b64_e32 v[114:115], 0
	v_mov_b64_e32 v[116:117], 0
	v_mov_b64_e32 v[118:119], 0
	v_mov_b64_e32 v[128:129], 0
	v_mov_b64_e32 v[130:131], 0
	v_mov_b64_e32 v[132:133], 0
	v_mov_b64_e32 v[134:135], 0
	s_branch .LBB0_154

; __device__ __forceinline__ int prow0(int pm) { return (pm >> 4) * LP + PADR + (pm & 15) * 256; }
; template <class Epi>
; __device__ __forceinline__ void gemm_phase(LAS unsigned char* lds, const bf16_t* Ag, const bf16_t* Btg, const int K, const int nM, const int nN, const Epi& E) {
;     ...
;         const int un = u + G; const bool has_next = un < nunits; const int pmn = has_next ? un % nM : pm, pnn = has_next ? un / nM : pn;
;         const char* nA = has_next ? (const char*)Ag + (size_t)prow0(pmn) * rstep : cA; const char* nB = has_next ? (const char*)Btg + (size_t)pnn * tstep : cB;
;     ...
; #pragma unroll
;         for (int a = 0; a < 2; ++a)
; #pragma unroll
;             for (int b = 0; b < 2; ++b)
; #pragma unroll
;                 for (int m = 0; m < 4; ++m)
; #pragma unroll
;                     for (int n = 0; n < 2; ++n) acc[a][b][m][n] = (f32x4){0.f, 0.f, 0.f, 0.f};
;         if (pmn != pm) par ^= 1;
;         u = un; pm = pmn; pn = pnn; cA = nA; cB = nB;
.LBB0_742:
	s_ashr_i32 s48, s12, 6
	s_ashr_i32 s49, s48, 31
	s_lshl_b64 s[14:15], s[48:49], 21
	s_add_u32 s50, s6, s14
	s_addc_u32 s51, s7, s15
	s_and_b64 s[14:15], s[54:55], exec
	s_cselect_b32 s15, s59, s51
	s_cselect_b32 s49, s58, s50
	s_cmp_eq_u32 s75, s74
	s_cselect_b64 s[60:61], -1, 0
	s_lshl_b32 s14, s72, 11
	s_xor_b32 s12, s14, 0x800
	s_add_i32 s53, s12, 0
	s_add_i32 s53, s53, 0x20000
	s_or_b64 s[54:55], s[54:55], s[60:61]
	s_add_u32 s77, s58, 0x100
	v_mov_b32_e32 v8, 0
	s_addc_u32 s78, s59, 0
	s_mov_b32 s79, -2
	v_mov_b32_e32 v9, v8
	s_waitcnt lgkmcnt(0)
	v_mov_b64_e32 v[10:11], 0
	v_mov_b64_e32 v[12:13], 0
	v_mov_b64_e32 v[14:15], 0
	v_mov_b64_e32 v[24:25], 0
	v_mov_b64_e32 v[26:27], 0
	v_mov_b64_e32 v[28:29], 0
	v_mov_b64_e32 v[30:31], 0
	v_mov_b64_e32 v[40:41], 0
	v_mov_b64_e32 v[42:43], 0
	v_mov_b64_e32 v[44:45], 0
	v_mov_b64_e32 v[46:47], 0
	v_mov_b64_e32 v[56:57], 0
	v_mov_b64_e32 v[58:59], 0
	v_mov_b64_e32 v[60:61], 0
	v_mov_b64_e32 v[62:63], 0
	v_mov_b64_e32 v[16:17], 0
	v_mov_b64_e32 v[18:19], 0
	v_mov_b64_e32 v[20:21], 0
	v_mov_b64_e32 v[22:23], 0
	v_mov_b64_e32 v[32:33], 0
	v_mov_b64_e32 v[34:35], 0
	v_mov_b64_e32 v[36:37], 0
	v_mov_b64_e32 v[38:39], 0
	v_mov_b64_e32 v[48:49], 0
	v_mov_b64_e32 v[50:51], 0
	v_mov_b64_e32 v[52:53], 0
	v_mov_b64_e32 v[54:55], 0
	v_mov_b64_e32 v[64:65], 0
	v_mov_b64_e32 v[66:67], 0
	v_mov_b64_e32 v[68:69], 0
	v_mov_b64_e32 v[70:71], 0
	v_mov_b64_e32 v[72:73], 0
	v_mov_b64_e32 v[74:75], 0
	v_mov_b64_e32 v[76:77], 0
	v_mov_b64_e32 v[78:79], 0
	v_mov_b64_e32 v[88:89], 0
	v_mov_b64_e32 v[90:91], 0
	v_mov_b64_e32 v[92:93], 0
	v_mov_b64_e32 v[94:95], 0
	v_mov_b64_e32 v[104:105], 0
	v_mov_b64_e32 v[106:107], 0
	v_mov_b64_e32 v[108:109], 0
	v_mov_b64_e32 v[110:111], 0
	v_mov_b64_e32 v[120:121], 0
	v_mov_b64_e32 v[122:123], 0
	v_mov_b64_e32 v[124:125], 0
	v_mov_b64_e32 v[126:127], 0
	v_mov_b64_e32 v[80:81], 0
	v_mov_b64_e32 v[82:83], 0
	v_mov_b64_e32 v[84:85], 0
	v_mov_b64_e32 v[86:87], 0
	v_mov_b64_e32 v[96:97], 0
	v_mov_b64_e32 v[98:99], 0
	v_mov_b64_e32 v[100:101], 0
	v_mov_b64_e32 v[102:103], 0
	v_mov_b64_e32 v[112:113], 0
	v_mov_b64_e32 v[114:115], 0
	v_mov_b64_e32 v[116:117], 0
	v_mov_b64_e32 v[118:119], 0
	v_mov_b64_e32 v[128:129], 0
	v_mov_b64_e32 v[130:131], 0
	v_mov_b64_e32 v[132:133], 0
	v_mov_b64_e32 v[134:135], 0
	s_branch .LBB0_745

; __device__ __forceinline__ int prow0(int pm) { return (pm >> 4) * LP + PADR + (pm & 15) * 256; }
; template <class Epi>
; __device__ __forceinline__ void gemm_phase(LAS unsigned char* lds, const bf16_t* Ag, const bf16_t* Btg, const int K, const int nM, const int nN, const Epi& E) {
;     ...
;         const int un = u + G; const bool has_next = un < nunits; const int pmn = has_next ? un % nM : pm, pnn = has_next ? un / nM : pn;
;         const char* nA = has_next ? (const char*)Ag + (size_t)prow0(pmn) * rstep : cA; const char* nB = has_next ? (const char*)Btg + (size_t)pnn * tstep : cB;
;     ...
; #pragma unroll
;         for (int a = 0; a < 2; ++a)
; #pragma unroll
;             for (int b = 0; b < 2; ++b)
; #pragma unroll
;                 for (int m = 0; m < 4; ++m)
; #pragma unroll
;                     for (int n = 0; n < 2; ++n) acc[a][b][m][n] = (f32x4){0.f, 0.f, 0.f, 0.f};
;         if (pmn != pm) par ^= 1;
;         u = un; pm = pmn; pn = pnn; cA = nA; cB = nB;
.LBB0_846:
	s_ashr_i32 s47, s26, 6
	s_and_b64 s[14:15], s[48:49], exec
	s_cselect_b32 s14, s69, s47
	s_ashr_i32 s15, s14, 31
	s_lshl_b64 s[14:15], s[14:15], 19
	s_add_u32 s44, s6, s14
	s_addc_u32 s45, s7, s15
	s_and_b64 s[14:15], s[48:49], exec
	s_cselect_b32 s14, s53, s45
	s_cselect_b32 s15, s52, s44
	s_cmp_eq_u32 s67, s68
	s_cselect_b64 s[54:55], -1, 0
	s_or_b64 s[54:55], s[42:43], s[54:55]
	v_lshlrev_b32_e32 v174, 11, v223
	s_or_b64 s[48:49], s[48:49], s[54:55]
	v_xor_b32_e32 v8, 0x800, v174
	s_add_u32 s70, s52, 0x100
	v_add_u32_e32 v8, 0, v8
	s_addc_u32 s71, s53, 0
	v_add_u32_e32 v128, 0x20000, v8
	s_add_u32 s50, s50, 0x40080
	v_mov_b32_e32 v8, 0
	s_addc_u32 s51, s51, 0
	s_mov_b32 s72, -2
	v_mov_b32_e32 v9, 0
	v_mov_b64_e32 v[10:11], 0
	v_mov_b64_e32 v[12:13], 0
	v_mov_b64_e32 v[14:15], 0
	v_mov_b64_e32 v[24:25], 0
	v_mov_b64_e32 v[26:27], 0
	v_mov_b64_e32 v[28:29], 0
	v_mov_b64_e32 v[30:31], 0
	v_mov_b64_e32 v[40:41], 0
	v_mov_b64_e32 v[42:43], 0
	v_mov_b64_e32 v[44:45], 0
	v_mov_b64_e32 v[46:47], 0
	v_mov_b64_e32 v[56:57], 0
	v_mov_b64_e32 v[58:59], 0
	v_mov_b64_e32 v[60:61], 0
	v_mov_b64_e32 v[62:63], 0
	v_mov_b64_e32 v[72:73], 0
	v_mov_b64_e32 v[74:75], 0
	v_mov_b64_e32 v[76:77], 0
	v_mov_b64_e32 v[78:79], 0
	v_mov_b64_e32 v[88:89], 0
	v_mov_b64_e32 v[90:91], 0
	v_mov_b64_e32 v[92:93], 0
	v_mov_b64_e32 v[94:95], 0
	v_mov_b64_e32 v[104:105], 0
	v_mov_b64_e32 v[106:107], 0
	v_mov_b64_e32 v[108:109], 0
	v_mov_b64_e32 v[110:111], 0
	v_mov_b64_e32 v[120:121], 0
	v_mov_b64_e32 v[122:123], 0
	v_mov_b64_e32 v[124:125], 0
	v_mov_b64_e32 v[126:127], 0
	v_mov_b64_e32 v[80:81], 0
	v_mov_b64_e32 v[82:83], 0
	v_mov_b64_e32 v[84:85], 0
	v_mov_b64_e32 v[86:87], 0
	v_mov_b64_e32 v[96:97], 0
	v_mov_b64_e32 v[98:99], 0
	v_mov_b64_e32 v[100:101], 0
	v_mov_b64_e32 v[102:103], 0
	v_mov_b64_e32 v[112:113], 0
	v_mov_b64_e32 v[114:115], 0
	v_mov_b64_e32 v[116:117], 0
	v_mov_b64_e32 v[118:119], 0
	v_mov_b64_e32 v[140:141], 0
	v_mov_b64_e32 v[142:143], 0
	v_mov_b64_e32 v[152:153], 0
	v_mov_b64_e32 v[154:155], 0
	v_mov_b64_e32 v[68:69], 0
	v_mov_b64_e32 v[70:71], 0
	v_mov_b64_e32 v[64:65], 0
	v_mov_b64_e32 v[66:67], 0
	v_mov_b64_e32 v[52:53], 0
	v_mov_b64_e32 v[54:55], 0
	v_mov_b64_e32 v[48:49], 0
	v_mov_b64_e32 v[50:51], 0
	v_mov_b64_e32 v[36:37], 0
	v_mov_b64_e32 v[38:39], 0
	v_mov_b64_e32 v[32:33], 0
	v_mov_b64_e32 v[34:35], 0
	v_mov_b64_e32 v[20:21], 0
	v_mov_b64_e32 v[22:23], 0
	v_mov_b64_e32 v[16:17], 0
	v_mov_b64_e32 v[18:19], 0
	s_branch .LBB0_849
